# gMLP unit start: two line-touch loads per wave (second half of the LayerNorm rows, gelu(u) values of the four channel groups)
# speedup vs baseline: 1.0147x; 1.0010x over previous
.LBB0_825:
	s_cmpk_gt_i32 s33, 0xff
	s_mov_b64 s[38:39], -1
	s_cbranch_scc0 .LBB0_879
	v_readlane_b32 s40, v254, 6
	v_readlane_b32 s41, v254, 7
	s_load_dwordx8 s[56:63], s[40:41], 0x58
	v_lshlrev_b64 v[2:3], 2, v[86:87]
	s_lshl_b32 s39, s33, 6
	s_and_b32 s38, s33, 1
	s_and_b32 s46, s39, 0x3f80
	s_waitcnt lgkmcnt(0)
	v_lshl_add_u64 v[6:7], s[56:57], 0, v[2:3]
	v_lshl_add_u64 v[14:15], s[58:59], 0, v[2:3]
	global_load_dwordx4 v[2:5], v[6:7], off
	s_nop 0
	global_load_dwordx4 v[6:9], v[6:7], off offset:16
	s_nop 0
	global_load_dwordx4 v[10:13], v[14:15], off
	s_nop 0
	global_load_dwordx4 v[14:17], v[14:15], off offset:16
	s_load_dwordx2 s[40:41], s[40:41], 0xa0
	s_mov_b64 s[42:43], 0xb000000
	s_add_i32 s46, s46, s74
	v_cmp_eq_u32_e64 s[38:39], s38, v143
	s_mov_b32 s44, 0
	s_waitcnt lgkmcnt(0)
	v_lshl_add_u64 v[18:19], v[86:87], 1, s[40:41]
	v_lshl_add_u64 v[46:47], v[18:19], 0, s[42:43]
	v_mov_b32_e32 v248, s40
	v_mov_b32_e32 v249, s41
	v_lshl_add_u64 v[248:249], v[248:249], 0, s[42:43]
	v_lshrrev_b32_e32 v246, 3, v202
	v_add_u32_e32 v246, s46, v246
	v_add_u32_e32 v246, 8, v246
	v_mul_u32_u24_e32 v246, 0x1800, v246
	v_and_b32_e32 v247, 7, v202
	v_lshl_add_u32 v246, v247, 7, v246
	v_mov_b32_e32 v247, 0
	v_lshl_add_u64 v[246:247], v[248:249], 0, v[246:247]
	global_load_dword v242, v[246:247], off offset:1024
	v_lshrrev_b32_e32 v246, 2, v202
	v_add_u32_e32 v246, s46, v246
	v_mul_u32_u24_e32 v246, 0x1800, v246
	v_and_b32_e32 v247, 3, v202
	v_lshl_add_u32 v246, v247, 7, v246
	s_and_b32 s47, s33, 1
	s_lshl_b32 s47, s47, 9
	v_add_u32_e32 v246, s47, v246
	v_mov_b32_e32 v247, 0
	v_lshl_add_u64 v[246:247], v[248:249], 0, v[246:247]
	global_load_dword v242, v[246:247], off
	s_mov_b64 s[42:43], -1
	s_branch .LBB0_828

.LBB0_2012:
	s_cmpk_gt_i32 s33, 0xff
	s_mov_b64 s[38:39], -1
	s_cbranch_scc0 .LBB0_2066
	s_load_dwordx8 s[40:47], s[68:69], 0x58
	v_lshlrev_b64 v[2:3], 2, v[86:87]
	s_lshl_b32 s39, s33, 6
	s_and_b32 s38, s33, 1
	s_and_b32 s50, s39, 0x3f80
	s_waitcnt lgkmcnt(0)
	v_lshl_add_u64 v[6:7], s[40:41], 0, v[2:3]
	v_lshl_add_u64 v[14:15], s[42:43], 0, v[2:3]
	global_load_dwordx4 v[2:5], v[6:7], off offset:2048
	s_nop 0
	global_load_dwordx4 v[6:9], v[6:7], off offset:2064
	s_nop 0
	global_load_dwordx4 v[10:13], v[14:15], off offset:2048
	s_nop 0
	global_load_dwordx4 v[14:17], v[14:15], off offset:2064
	s_load_dwordx2 s[40:41], s[68:69], 0xa0
	s_mov_b64 s[42:43], 0xb000000
	s_add_i32 s50, s50, s70
	v_cmp_eq_u32_e64 s[38:39], s38, v143
	s_mov_b32 s48, 0
	s_waitcnt lgkmcnt(0)
	v_lshl_add_u64 v[18:19], v[86:87], 1, s[40:41]
	v_lshl_add_u64 v[46:47], v[18:19], 0, s[42:43]
	v_mov_b32_e32 v248, s40
	v_mov_b32_e32 v249, s41
	v_lshl_add_u64 v[248:249], v[248:249], 0, s[42:43]
	v_lshrrev_b32_e32 v246, 3, v202
	v_add_u32_e32 v246, s50, v246
	v_add_u32_e32 v246, 8, v246
	v_mul_u32_u24_e32 v246, 0x1800, v246
	v_and_b32_e32 v247, 7, v202
	v_lshl_add_u32 v246, v247, 7, v246
	v_mov_b32_e32 v247, 0
	v_lshl_add_u64 v[246:247], v[248:249], 0, v[246:247]
	global_load_dword v242, v[246:247], off offset:1024
	v_lshrrev_b32_e32 v246, 2, v202
	v_add_u32_e32 v246, s50, v246
	v_mul_u32_u24_e32 v246, 0x1800, v246
	v_and_b32_e32 v247, 3, v202
	v_lshl_add_u32 v246, v247, 7, v246
	s_and_b32 s51, s33, 1
	s_lshl_b32 s51, s51, 9
	v_add_u32_e32 v246, s51, v246
	v_mov_b32_e32 v247, 0
	v_lshl_add_u64 v[246:247], v[248:249], 0, v[246:247]
	global_load_dword v242, v[246:247], off
	s_mov_b64 s[42:43], -1
	s_branch .LBB0_2015
